# SWIGLU epilogue stores widened to 16 B per lane (v_permlane16_swap pairs), 8 instead of 16 store instructions per wave
# speedup vs baseline: 1.0247x; 1.0247x over previous
; __device__ __forceinline__ u32x2 pk4(f32x4 v) { u32x2 r; r.x = cvt_pk_bf16(v[0], v[1]); r.y = cvt_pk_bf16(v[2], v[3]); return r; }
; __device__ __forceinline__ float sigmoidf_(float v) { return __builtin_amdgcn_rcpf(1.f + __builtin_amdgcn_exp2f(-1.4426950408889634f * v)); }
; template <int K>
; __device__ __forceinline__ void epilogue(const f32x4 (&acc)[2][2][4][2], const Unit& u, const EpiDesc& E, const Ctx& C, int wr, int wc, int fr, int fq) {
;     ...
;     if (K == EK_SWIGLU || K == EK_PROJ) {
;         float rstd[2][4];
; #pragma unroll
;         for (int ai = 0; ai < 2; ++ai)
; #pragma unroll
;             for (int m = 0; m < 4; ++m) rstd[ai][m] = E.rss_in[row0 + 128 * ai + 16 * m];
; #pragma unroll
;         for (int ai = 0; ai < 2; ++ai)
; #pragma unroll
;             for (int m = 0; m < 4; ++m) rstd[ai][m] = __builtin_amdgcn_rsqf(rstd[ai][m] * (1.f / 1024.f) + RMS_EPS);
;         if (K == EK_SWIGLU) {
; #pragma unroll
;             for (int ai = 0; ai < 2; ++ai)
; #pragma unroll
;                 for (int m = 0; m < 4; ++m) {
;                     const int row = row0 + 128 * ai + 16 * m;
; #pragma unroll
;                     for (int bj = 0; bj < 2; ++bj) {
;                         const f32x4 g = acc[ai][bj][m][0] * rstd[ai][m], up = acc[ai][bj][m][1] * rstd[ai][m];
;                         f32x4 a;
; #pragma unroll
;                         for (int i = 0; i < 4; ++i) a[i] = g[i] * sigmoidf_(g[i]) * up[i];
;                         const int j = 16 * (8 * u.pn + 4 * bj + wc) + 4 * fq;
;                         *(u32x2*)(C.ACT + (size_t)row * DFF + j) = pk4(a);
;                     }
.Lswg_main:
	v_readlane_b32 s2, v254, 31
	v_readlane_b32 s3, v254, 32
	v_lshl_or_b32 v133, s86, 7, v176
	v_mul_u32_u24_e32 v130, 0x1600, v0
	v_lshl_add_u32 v130, v133, 1, v130
	v_and_b32_e32 v131, 16, v233
	v_lshrrev_b32_e32 v133, 1, v131
	v_mad_u32_u24 v131, v131, 7, v133
	v_add_u32_e32 v130, v130, v131
	s_waitcnt lgkmcnt(0)
	v_pk_mul_f32 v[126:127], v[122:123], v[126:127]
	v_pk_mul_f32 v[128:129], v[124:125], v[128:129]
	v_pk_mul_f32 v[118:119], v[114:115], v[118:119]
	v_pk_mul_f32 v[120:121], v[116:117], v[120:121]
	v_pk_mul_f32 v[110:111], v[106:107], v[110:111]
	v_pk_mul_f32 v[112:113], v[108:109], v[112:113]
	v_pk_mul_f32 v[102:103], v[98:99], v[102:103]
	v_pk_mul_f32 v[104:105], v[100:101], v[104:105]
	v_pk_mul_f32 v[94:95], v[90:91], v[94:95]
	v_pk_mul_f32 v[96:97], v[92:93], v[96:97]
	v_pk_mul_f32 v[86:87], v[82:83], v[86:87]
	v_pk_mul_f32 v[88:89], v[84:85], v[88:89]
	v_pk_mul_f32 v[78:79], v[74:75], v[78:79]
	v_pk_mul_f32 v[80:81], v[76:77], v[80:81]
	v_pk_mul_f32 v[70:71], v[66:67], v[70:71]
	v_pk_mul_f32 v[72:73], v[68:69], v[72:73]
	v_pk_mul_f32 v[62:63], v[58:59], v[62:63]
	v_pk_mul_f32 v[64:65], v[60:61], v[64:65]
	v_pk_mul_f32 v[54:55], v[50:51], v[54:55]
	v_pk_mul_f32 v[56:57], v[52:53], v[56:57]
	v_pk_mul_f32 v[46:47], v[42:43], v[46:47]
	v_pk_mul_f32 v[48:49], v[44:45], v[48:49]
	v_pk_mul_f32 v[38:39], v[34:35], v[38:39]
	v_pk_mul_f32 v[40:41], v[36:37], v[40:41]
	v_pk_mul_f32 v[30:31], v[26:27], v[30:31]
	v_pk_mul_f32 v[32:33], v[28:29], v[32:33]
	v_pk_mul_f32 v[22:23], v[18:19], v[22:23]
	v_pk_mul_f32 v[24:25], v[20:21], v[24:25]
	v_pk_mul_f32 v[14:15], v[10:11], v[14:15]
	v_pk_mul_f32 v[16:17], v[12:13], v[16:17]
	v_pk_mul_f32 v[2:3], v[6:7], v[2:3]
	v_pk_mul_f32 v[4:5], v[8:9], v[4:5]
	s_waitcnt vmcnt(0)
	v_fmamk_f32 v145, v144, 0x3a800000, v231
	v_fmamk_f32 v147, v146, 0x3a800000, v231
	v_fmamk_f32 v149, v148, 0x3a800000, v231
	v_fmamk_f32 v151, v150, 0x3a800000, v231
	v_fmamk_f32 v153, v152, 0x3a800000, v231
	v_fmamk_f32 v155, v154, 0x3a800000, v231
	v_fmamk_f32 v157, v156, 0x3a800000, v231
	v_fmamk_f32 v159, v158, 0x3a800000, v231
	v_rsq_f32_e32 v144, v145
	v_rsq_f32_e32 v146, v147
	v_rsq_f32_e32 v148, v149
	v_rsq_f32_e32 v150, v151
	v_rsq_f32_e32 v152, v153
	v_rsq_f32_e32 v154, v155
	v_rsq_f32_e32 v156, v157
	v_rsq_f32_e32 v158, v159
	v_mul_f32_e32 v144, 0xbfb8aa3b, v144
	v_mul_f32_e32 v146, 0xbfb8aa3b, v146
	v_mul_f32_e32 v148, 0xbfb8aa3b, v148
	v_mul_f32_e32 v150, 0xbfb8aa3b, v150
	v_mul_f32_e32 v152, 0xbfb8aa3b, v152
	v_mul_f32_e32 v154, 0xbfb8aa3b, v154
	v_mul_f32_e32 v156, 0xbfb8aa3b, v156
	v_mul_f32_e32 v158, 0xbfb8aa3b, v158
	v_pk_mul_f32 v[122:123], v[122:123], v[144:145] op_sel_hi:[1,0]
	v_pk_mul_f32 v[124:125], v[124:125], v[144:145] op_sel_hi:[1,0]
	v_pk_mul_f32 v[114:115], v[114:115], v[144:145] op_sel_hi:[1,0]
	v_pk_mul_f32 v[116:117], v[116:117], v[144:145] op_sel_hi:[1,0]
	v_exp_f32_e32 v122, v122
	v_exp_f32_e32 v123, v123
	v_exp_f32_e32 v124, v124
	v_exp_f32_e32 v125, v125
	v_exp_f32_e32 v114, v114
	v_exp_f32_e32 v115, v115
	v_exp_f32_e32 v116, v116
	v_exp_f32_e32 v117, v117
	v_fma_f32 v122, v122, v145, v145
	v_fma_f32 v123, v123, v145, v145
	v_fma_f32 v124, v124, v145, v145
	v_fma_f32 v125, v125, v145, v145
	v_fma_f32 v114, v114, v145, v145
	v_fma_f32 v115, v115, v145, v145
	v_fma_f32 v116, v116, v145, v145
	v_fma_f32 v117, v117, v145, v145
	v_rcp_f32_e32 v122, v122
	v_rcp_f32_e32 v123, v123
	v_rcp_f32_e32 v124, v124
	v_rcp_f32_e32 v125, v125
	v_rcp_f32_e32 v114, v114
	v_rcp_f32_e32 v115, v115
	v_rcp_f32_e32 v116, v116
	v_rcp_f32_e32 v117, v117
	v_pk_mul_f32 v[126:127], v[126:127], v[122:123]
	v_pk_mul_f32 v[128:129], v[128:129], v[124:125]
	v_pk_mul_f32 v[118:119], v[118:119], v[114:115]
	v_pk_mul_f32 v[120:121], v[120:121], v[116:117]
	v_cvt_pk_bf16_f32 v122, v126, v127
	v_cvt_pk_bf16_f32 v123, v128, v129
	v_cvt_pk_bf16_f32 v124, v118, v119
	v_cvt_pk_bf16_f32 v125, v120, v121
	v_pk_mul_f32 v[106:107], v[106:107], v[146:147] op_sel_hi:[1,0]
	v_pk_mul_f32 v[108:109], v[108:109], v[146:147] op_sel_hi:[1,0]
	v_pk_mul_f32 v[98:99], v[98:99], v[146:147] op_sel_hi:[1,0]
	v_pk_mul_f32 v[100:101], v[100:101], v[146:147] op_sel_hi:[1,0]
	v_permlane16_swap_b32_e32 v122, v124
	v_permlane16_swap_b32_e32 v123, v125
	global_store_dwordx4 v130, v[122:125], s[2:3]
	v_add_u32_e32 v130, 0x16000, v130
	v_exp_f32_e32 v106, v106
	v_exp_f32_e32 v107, v107
	v_exp_f32_e32 v108, v108
	v_exp_f32_e32 v109, v109
	v_exp_f32_e32 v98, v98
	v_exp_f32_e32 v99, v99
	v_exp_f32_e32 v100, v100
	v_exp_f32_e32 v101, v101
	v_fma_f32 v106, v106, v147, v147
	v_fma_f32 v107, v107, v147, v147
	v_fma_f32 v108, v108, v147, v147
	v_fma_f32 v109, v109, v147, v147
	v_fma_f32 v98, v98, v147, v147
	v_fma_f32 v99, v99, v147, v147
	v_fma_f32 v100, v100, v147, v147
	v_fma_f32 v101, v101, v147, v147
	v_rcp_f32_e32 v106, v106
	v_rcp_f32_e32 v107, v107
	v_rcp_f32_e32 v108, v108
	v_rcp_f32_e32 v109, v109
	v_rcp_f32_e32 v98, v98
	v_rcp_f32_e32 v99, v99
	v_rcp_f32_e32 v100, v100
	v_rcp_f32_e32 v101, v101
	v_pk_mul_f32 v[110:111], v[110:111], v[106:107]
	v_pk_mul_f32 v[112:113], v[112:113], v[108:109]
	v_pk_mul_f32 v[102:103], v[102:103], v[98:99]
	v_pk_mul_f32 v[104:105], v[104:105], v[100:101]
	v_cvt_pk_bf16_f32 v106, v110, v111
	v_cvt_pk_bf16_f32 v107, v112, v113
	v_cvt_pk_bf16_f32 v108, v102, v103
	v_cvt_pk_bf16_f32 v109, v104, v105
	v_pk_mul_f32 v[90:91], v[90:91], v[148:149] op_sel_hi:[1,0]
	v_pk_mul_f32 v[92:93], v[92:93], v[148:149] op_sel_hi:[1,0]
	v_pk_mul_f32 v[82:83], v[82:83], v[148:149] op_sel_hi:[1,0]
	v_pk_mul_f32 v[84:85], v[84:85], v[148:149] op_sel_hi:[1,0]
	v_permlane16_swap_b32_e32 v106, v108
	v_permlane16_swap_b32_e32 v107, v109
; __device__ __forceinline__ u32x2 pk4(f32x4 v) { u32x2 r; r.x = cvt_pk_bf16(v[0], v[1]); r.y = cvt_pk_bf16(v[2], v[3]); return r; }
; __device__ __forceinline__ float sigmoidf_(float v) { return __builtin_amdgcn_rcpf(1.f + __builtin_amdgcn_exp2f(-1.4426950408889634f * v)); }
; template <int K>
; __device__ __forceinline__ void epilogue(const f32x4 (&acc)[2][2][4][2], const Unit& u, const EpiDesc& E, const Ctx& C, int wr, int wc, int fr, int fq) {
;     ...
;         if (K == EK_SWIGLU) {
; #pragma unroll
;             for (int ai = 0; ai < 2; ++ai)
; #pragma unroll
;                 for (int m = 0; m < 4; ++m) {
;                     const int row = row0 + 128 * ai + 16 * m;
; #pragma unroll
;                     for (int bj = 0; bj < 2; ++bj) {
;                         const f32x4 g = acc[ai][bj][m][0] * rstd[ai][m], up = acc[ai][bj][m][1] * rstd[ai][m];
;                         f32x4 a;
; #pragma unroll
;                         for (int i = 0; i < 4; ++i) a[i] = g[i] * sigmoidf_(g[i]) * up[i];
;                         const int j = 16 * (8 * u.pn + 4 * bj + wc) + 4 * fq;
;                         *(u32x2*)(C.ACT + (size_t)row * DFF + j) = pk4(a);
;                     }
	global_store_dwordx4 v130, v[106:109], s[2:3]
	v_add_u32_e32 v130, 0x16000, v130
	v_exp_f32_e32 v90, v90
	v_exp_f32_e32 v91, v91
	v_exp_f32_e32 v92, v92
	v_exp_f32_e32 v93, v93
	v_exp_f32_e32 v82, v82
	v_exp_f32_e32 v83, v83
	v_exp_f32_e32 v84, v84
	v_exp_f32_e32 v85, v85
	v_fma_f32 v90, v90, v149, v149
	v_fma_f32 v91, v91, v149, v149
	v_fma_f32 v92, v92, v149, v149
	v_fma_f32 v93, v93, v149, v149
	v_fma_f32 v82, v82, v149, v149
	v_fma_f32 v83, v83, v149, v149
	v_fma_f32 v84, v84, v149, v149
	v_fma_f32 v85, v85, v149, v149
	v_rcp_f32_e32 v90, v90
	v_rcp_f32_e32 v91, v91
	v_rcp_f32_e32 v92, v92
	v_rcp_f32_e32 v93, v93
	v_rcp_f32_e32 v82, v82
	v_rcp_f32_e32 v83, v83
	v_rcp_f32_e32 v84, v84
	v_rcp_f32_e32 v85, v85
	v_pk_mul_f32 v[94:95], v[94:95], v[90:91]
	v_pk_mul_f32 v[96:97], v[96:97], v[92:93]
	v_pk_mul_f32 v[86:87], v[86:87], v[82:83]
	v_pk_mul_f32 v[88:89], v[88:89], v[84:85]
	v_cvt_pk_bf16_f32 v90, v94, v95
	v_cvt_pk_bf16_f32 v91, v96, v97
	v_cvt_pk_bf16_f32 v92, v86, v87
	v_cvt_pk_bf16_f32 v93, v88, v89
	v_pk_mul_f32 v[74:75], v[74:75], v[150:151] op_sel_hi:[1,0]
	v_pk_mul_f32 v[76:77], v[76:77], v[150:151] op_sel_hi:[1,0]
	v_pk_mul_f32 v[66:67], v[66:67], v[150:151] op_sel_hi:[1,0]
	v_pk_mul_f32 v[68:69], v[68:69], v[150:151] op_sel_hi:[1,0]
	v_permlane16_swap_b32_e32 v90, v92
	v_permlane16_swap_b32_e32 v91, v93
	global_store_dwordx4 v130, v[90:93], s[2:3]
	v_add_u32_e32 v130, 0x16000, v130
	v_exp_f32_e32 v74, v74
	v_exp_f32_e32 v75, v75
	v_exp_f32_e32 v76, v76
	v_exp_f32_e32 v77, v77
	v_exp_f32_e32 v66, v66
	v_exp_f32_e32 v67, v67
	v_exp_f32_e32 v68, v68
	v_exp_f32_e32 v69, v69
	v_fma_f32 v74, v74, v151, v151
	v_fma_f32 v75, v75, v151, v151
	v_fma_f32 v76, v76, v151, v151
	v_fma_f32 v77, v77, v151, v151
	v_fma_f32 v66, v66, v151, v151
	v_fma_f32 v67, v67, v151, v151
	v_fma_f32 v68, v68, v151, v151
	v_fma_f32 v69, v69, v151, v151
	v_rcp_f32_e32 v74, v74
	v_rcp_f32_e32 v75, v75
	v_rcp_f32_e32 v76, v76
	v_rcp_f32_e32 v77, v77
	v_rcp_f32_e32 v66, v66
	v_rcp_f32_e32 v67, v67
	v_rcp_f32_e32 v68, v68
	v_rcp_f32_e32 v69, v69
	v_pk_mul_f32 v[78:79], v[78:79], v[74:75]
	v_pk_mul_f32 v[80:81], v[80:81], v[76:77]
	v_pk_mul_f32 v[70:71], v[70:71], v[66:67]
	v_pk_mul_f32 v[72:73], v[72:73], v[68:69]
	v_cvt_pk_bf16_f32 v74, v78, v79
	v_cvt_pk_bf16_f32 v75, v80, v81
	v_cvt_pk_bf16_f32 v76, v70, v71
	v_cvt_pk_bf16_f32 v77, v72, v73
	v_pk_mul_f32 v[58:59], v[58:59], v[152:153] op_sel_hi:[1,0]
	v_pk_mul_f32 v[60:61], v[60:61], v[152:153] op_sel_hi:[1,0]
	v_pk_mul_f32 v[50:51], v[50:51], v[152:153] op_sel_hi:[1,0]
	v_pk_mul_f32 v[52:53], v[52:53], v[152:153] op_sel_hi:[1,0]
	v_permlane16_swap_b32_e32 v74, v76
	v_permlane16_swap_b32_e32 v75, v77
	global_store_dwordx4 v130, v[74:77], s[2:3]
	v_add_u32_e32 v130, 0x6e000, v130
	v_exp_f32_e32 v58, v58
	v_exp_f32_e32 v59, v59
	v_exp_f32_e32 v60, v60
	v_exp_f32_e32 v61, v61
	v_exp_f32_e32 v50, v50
	v_exp_f32_e32 v51, v51
	v_exp_f32_e32 v52, v52
	v_exp_f32_e32 v53, v53
	v_fma_f32 v58, v58, v153, v153
	v_fma_f32 v59, v59, v153, v153
	v_fma_f32 v60, v60, v153, v153
	v_fma_f32 v61, v61, v153, v153
	v_fma_f32 v50, v50, v153, v153
	v_fma_f32 v51, v51, v153, v153
	v_fma_f32 v52, v52, v153, v153
	v_fma_f32 v53, v53, v153, v153
	v_rcp_f32_e32 v58, v58
	v_rcp_f32_e32 v59, v59
	v_rcp_f32_e32 v60, v60
	v_rcp_f32_e32 v61, v61
	v_rcp_f32_e32 v50, v50
	v_rcp_f32_e32 v51, v51
	v_rcp_f32_e32 v52, v52
	v_rcp_f32_e32 v53, v53
	v_pk_mul_f32 v[62:63], v[62:63], v[58:59]
	v_pk_mul_f32 v[64:65], v[64:65], v[60:61]
	v_pk_mul_f32 v[54:55], v[54:55], v[50:51]
	v_pk_mul_f32 v[56:57], v[56:57], v[52:53]
	v_cvt_pk_bf16_f32 v58, v62, v63
	v_cvt_pk_bf16_f32 v59, v64, v65
	v_cvt_pk_bf16_f32 v60, v54, v55
	v_cvt_pk_bf16_f32 v61, v56, v57
	v_pk_mul_f32 v[42:43], v[42:43], v[154:155] op_sel_hi:[1,0]
	v_pk_mul_f32 v[44:45], v[44:45], v[154:155] op_sel_hi:[1,0]
	v_pk_mul_f32 v[34:35], v[34:35], v[154:155] op_sel_hi:[1,0]
	v_pk_mul_f32 v[36:37], v[36:37], v[154:155] op_sel_hi:[1,0]
; __device__ __forceinline__ u32x2 pk4(f32x4 v) { u32x2 r; r.x = cvt_pk_bf16(v[0], v[1]); r.y = cvt_pk_bf16(v[2], v[3]); return r; }
; __device__ __forceinline__ float sigmoidf_(float v) { return __builtin_amdgcn_rcpf(1.f + __builtin_amdgcn_exp2f(-1.4426950408889634f * v)); }
; template <int K>
; __device__ __forceinline__ void epilogue(const f32x4 (&acc)[2][2][4][2], const Unit& u, const EpiDesc& E, const Ctx& C, int wr, int wc, int fr, int fq) {
;     ...
;         if (K == EK_SWIGLU) {
; #pragma unroll
;             for (int ai = 0; ai < 2; ++ai)
; #pragma unroll
;                 for (int m = 0; m < 4; ++m) {
;                     const int row = row0 + 128 * ai + 16 * m;
; #pragma unroll
;                     for (int bj = 0; bj < 2; ++bj) {
;                         const f32x4 g = acc[ai][bj][m][0] * rstd[ai][m], up = acc[ai][bj][m][1] * rstd[ai][m];
;                         f32x4 a;
; #pragma unroll
;                         for (int i = 0; i < 4; ++i) a[i] = g[i] * sigmoidf_(g[i]) * up[i];
;                         const int j = 16 * (8 * u.pn + 4 * bj + wc) + 4 * fq;
;                         *(u32x2*)(C.ACT + (size_t)row * DFF + j) = pk4(a);
;                     }
	v_permlane16_swap_b32_e32 v58, v60
	v_permlane16_swap_b32_e32 v59, v61
	global_store_dwordx4 v130, v[58:61], s[2:3]
	v_add_u32_e32 v130, 0x16000, v130
	v_exp_f32_e32 v42, v42
	v_exp_f32_e32 v43, v43
	v_exp_f32_e32 v44, v44
	v_exp_f32_e32 v45, v45
	v_exp_f32_e32 v34, v34
	v_exp_f32_e32 v35, v35
	v_exp_f32_e32 v36, v36
	v_exp_f32_e32 v37, v37
	v_fma_f32 v42, v42, v155, v155
	v_fma_f32 v43, v43, v155, v155
	v_fma_f32 v44, v44, v155, v155
	v_fma_f32 v45, v45, v155, v155
	v_fma_f32 v34, v34, v155, v155
	v_fma_f32 v35, v35, v155, v155
	v_fma_f32 v36, v36, v155, v155
	v_fma_f32 v37, v37, v155, v155
	v_rcp_f32_e32 v42, v42
	v_rcp_f32_e32 v43, v43
	v_rcp_f32_e32 v44, v44
	v_rcp_f32_e32 v45, v45
	v_rcp_f32_e32 v34, v34
	v_rcp_f32_e32 v35, v35
	v_rcp_f32_e32 v36, v36
	v_rcp_f32_e32 v37, v37
	v_pk_mul_f32 v[46:47], v[46:47], v[42:43]
	v_pk_mul_f32 v[48:49], v[48:49], v[44:45]
	v_pk_mul_f32 v[38:39], v[38:39], v[34:35]
	v_pk_mul_f32 v[40:41], v[40:41], v[36:37]
	v_cvt_pk_bf16_f32 v42, v46, v47
	v_cvt_pk_bf16_f32 v43, v48, v49
	v_cvt_pk_bf16_f32 v44, v38, v39
	v_cvt_pk_bf16_f32 v45, v40, v41
	v_pk_mul_f32 v[26:27], v[26:27], v[156:157] op_sel_hi:[1,0]
	v_pk_mul_f32 v[28:29], v[28:29], v[156:157] op_sel_hi:[1,0]
	v_pk_mul_f32 v[18:19], v[18:19], v[156:157] op_sel_hi:[1,0]
	v_pk_mul_f32 v[20:21], v[20:21], v[156:157] op_sel_hi:[1,0]
	v_permlane16_swap_b32_e32 v42, v44
	v_permlane16_swap_b32_e32 v43, v45
	global_store_dwordx4 v130, v[42:45], s[2:3]
	v_add_u32_e32 v130, 0x16000, v130
	v_exp_f32_e32 v26, v26
	v_exp_f32_e32 v27, v27
	v_exp_f32_e32 v28, v28
	v_exp_f32_e32 v29, v29
	v_exp_f32_e32 v18, v18
	v_exp_f32_e32 v19, v19
	v_exp_f32_e32 v20, v20
	v_exp_f32_e32 v21, v21
	v_fma_f32 v26, v26, v157, v157
	v_fma_f32 v27, v27, v157, v157
	v_fma_f32 v28, v28, v157, v157
	v_fma_f32 v29, v29, v157, v157
	v_fma_f32 v18, v18, v157, v157
	v_fma_f32 v19, v19, v157, v157
	v_fma_f32 v20, v20, v157, v157
	v_fma_f32 v21, v21, v157, v157
	v_rcp_f32_e32 v26, v26
	v_rcp_f32_e32 v27, v27
	v_rcp_f32_e32 v28, v28
	v_rcp_f32_e32 v29, v29
	v_rcp_f32_e32 v18, v18
	v_rcp_f32_e32 v19, v19
	v_rcp_f32_e32 v20, v20
	v_rcp_f32_e32 v21, v21
	v_pk_mul_f32 v[30:31], v[30:31], v[26:27]
	v_pk_mul_f32 v[32:33], v[32:33], v[28:29]
	v_pk_mul_f32 v[22:23], v[22:23], v[18:19]
	v_pk_mul_f32 v[24:25], v[24:25], v[20:21]
	v_cvt_pk_bf16_f32 v26, v30, v31
	v_cvt_pk_bf16_f32 v27, v32, v33
	v_cvt_pk_bf16_f32 v28, v22, v23
	v_cvt_pk_bf16_f32 v29, v24, v25
	v_pk_mul_f32 v[10:11], v[10:11], v[158:159] op_sel_hi:[1,0]
	v_pk_mul_f32 v[12:13], v[12:13], v[158:159] op_sel_hi:[1,0]
	v_pk_mul_f32 v[6:7], v[6:7], v[158:159] op_sel_hi:[1,0]
	v_pk_mul_f32 v[8:9], v[8:9], v[158:159] op_sel_hi:[1,0]
	v_permlane16_swap_b32_e32 v26, v28
	v_permlane16_swap_b32_e32 v27, v29
	global_store_dwordx4 v130, v[26:29], s[2:3]
	v_add_u32_e32 v130, 0x16000, v130
	v_exp_f32_e32 v10, v10
	v_exp_f32_e32 v11, v11
	v_exp_f32_e32 v12, v12
	v_exp_f32_e32 v13, v13
	v_exp_f32_e32 v6, v6
	v_exp_f32_e32 v7, v7
	v_exp_f32_e32 v8, v8
	v_exp_f32_e32 v9, v9
	v_fma_f32 v10, v10, v159, v159
	v_fma_f32 v11, v11, v159, v159
	v_fma_f32 v12, v12, v159, v159
	v_fma_f32 v13, v13, v159, v159
	v_fma_f32 v6, v6, v159, v159
	v_fma_f32 v7, v7, v159, v159
	v_fma_f32 v8, v8, v159, v159
	v_fma_f32 v9, v9, v159, v159
	v_rcp_f32_e32 v10, v10
	v_rcp_f32_e32 v11, v11
	v_rcp_f32_e32 v12, v12
	v_rcp_f32_e32 v13, v13
	v_rcp_f32_e32 v6, v6
	v_rcp_f32_e32 v7, v7
	v_rcp_f32_e32 v8, v8
	v_rcp_f32_e32 v9, v9
	v_pk_mul_f32 v[14:15], v[14:15], v[10:11]
	v_pk_mul_f32 v[16:17], v[16:17], v[12:13]
	v_pk_mul_f32 v[2:3], v[2:3], v[6:7]
	v_pk_mul_f32 v[4:5], v[4:5], v[8:9]
	v_cvt_pk_bf16_f32 v10, v14, v15
	v_cvt_pk_bf16_f32 v11, v16, v17
	v_cvt_pk_bf16_f32 v12, v2, v3
	v_cvt_pk_bf16_f32 v13, v4, v5
	s_nop 1
	v_permlane16_swap_b32_e32 v10, v12
	v_permlane16_swap_b32_e32 v11, v13
	global_store_dwordx4 v130, v[10:13], s[2:3]
	s_and_b64 vcc, exec, s[40:41]
	s_mov_b64 s[2:3], -1
	s_cbranch_vccnz .LBB0_230
